# G4 (ffn_in) main loop: LDS-DMA source pointers advanced in place, M0 formed on the scalar unit (28 -> 8 vector ops per 2 slices)
# speedup vs baseline: 1.0170x; 1.0037x over previous
.LBB0_179:
	s_lshl_b32 s17, s8, 6
	v_mov_b32_e32 v10, v202
	s_and_b32 s17, s17, 0x1f00
	s_add_i32 s19, s17, 0xffffff00
	v_bfe_u32 v196, v10, 4, 2
	v_ashrrev_i32_e32 v197, 6, v10
	v_bfe_u32 v4, v10, 2, 4
	v_bitop3_b32 v0, v196, v10, 3 bitop3:0x78
	v_readlane_b32 s20, v254, 49
	v_or_b32_e32 v11, s19, v4
	v_lshlrev_b32_e32 v0, 4, v0
	v_or_b32_e32 v12, s22, v4
	v_readlane_b32 s21, v254, 50
	v_cmp_gt_i32_e32 vcc, 16, v197
	v_lshl_add_u64 v[2:3], s[40:41], 0, v[0:1]
	v_lshl_add_u64 v[4:5], s[20:21], 0, v[0:1]
	v_lshlrev_b32_e32 v0, 4, v197
	v_cndmask_b32_e32 v8, v11, v12, vcc
	v_add_u32_e32 v8, v8, v0
	v_ashrrev_i32_e32 v9, 31, v8
	v_cndmask_b32_e32 v7, v3, v5, vcc
	v_cndmask_b32_e32 v6, v2, v4, vcc
	v_lshlrev_b64 v[8:9], 11, v[8:9]
	v_cmp_gt_i32_e32 vcc, 8, v197
	v_lshl_add_u64 v[186:187], v[6:7], 0, v[8:9]
	s_movk_i32 s19, 0x80
	v_cndmask_b32_e32 v8, v11, v12, vcc
	v_add3_u32 v8, v0, v8, s19
	v_ashrrev_i32_e32 v9, 31, v8
	v_cndmask_b32_e32 v7, v3, v5, vcc
	v_cndmask_b32_e32 v6, v2, v4, vcc
	v_lshlrev_b64 v[8:9], 11, v[8:9]
	v_cmp_gt_i32_e32 vcc, 0, v197
	v_lshl_add_u64 v[188:189], v[6:7], 0, v[8:9]
	s_movk_i32 s19, 0x100
	v_cndmask_b32_e32 v8, v11, v12, vcc
	v_add3_u32 v8, v0, v8, s19
	v_ashrrev_i32_e32 v9, 31, v8
	v_cndmask_b32_e32 v7, v3, v5, vcc
	v_cndmask_b32_e32 v6, v2, v4, vcc
	v_lshlrev_b64 v[8:9], 11, v[8:9]
	v_cmp_gt_i32_e32 vcc, -8, v197
	v_and_b32_e32 v194, 63, v10
	v_lshl_add_u64 v[190:191], v[6:7], 0, v[8:9]
	v_cndmask_b32_e32 v6, v11, v12, vcc
	s_movk_i32 s19, 0x180
	v_cndmask_b32_e32 v2, v2, v4, vcc
	v_add3_u32 v4, v0, v6, s19
	v_lshlrev_b32_e32 v0, 4, v194
	v_lshl_or_b32 v198, v197, 10, v0
	v_add_u32_e32 v0, 0x2000, v198
	v_readfirstlane_b32 s19, v198
	s_mov_b32 m0, s19
	s_mov_b32 s88, s19
	v_readfirstlane_b32 s19, v0
	v_add_u32_e32 v0, 0x4000, v198
	v_cndmask_b32_e32 v3, v3, v5, vcc
	v_ashrrev_i32_e32 v5, 31, v4
	s_barrier
	global_load_lds_dwordx4 v[186:187], off
	s_mov_b32 m0, s19
	v_readfirstlane_b32 s19, v0
	v_add_u32_e32 v0, 0x6000, v198
	v_lshlrev_b64 v[4:5], 11, v[4:5]
	global_load_lds_dwordx4 v[188:189], off
	s_mov_b32 m0, s19
	v_readfirstlane_b32 s19, v0
	v_add_u32_e32 v0, 0x8000, v198
	v_lshl_add_u64 v[192:193], v[2:3], 0, v[4:5]
	global_load_lds_dwordx4 v[190:191], off
	s_mov_b32 m0, s19
	v_readfirstlane_b32 s19, v0
	v_add_u32_e32 v0, 0xa000, v198
	global_load_lds_dwordx4 v[192:193], off
	v_lshl_add_u64 v[2:3], v[186:187], 0, 64
	s_mov_b32 m0, s19
	v_readfirstlane_b32 s19, v0
	v_add_u32_e32 v0, 0xc000, v198
	global_load_lds_dwordx4 v[2:3], off
	v_lshl_add_u64 v[2:3], v[188:189], 0, 64
	s_mov_b32 m0, s19
	v_readfirstlane_b32 s19, v0
	v_add_u32_e32 v0, 0xe000, v198
	global_load_lds_dwordx4 v[2:3], off
	v_lshl_add_u64 v[2:3], v[190:191], 0, 64
	s_mov_b32 m0, s19
	v_readfirstlane_b32 s19, v0
	v_add_u32_e32 v0, 0x10000, v198
	global_load_lds_dwordx4 v[2:3], off
	v_lshl_add_u64 v[2:3], v[192:193], 0, 64
	s_mov_b32 m0, s19
	v_readfirstlane_b32 s19, v0
	v_add_u32_e32 v0, 0x12000, v198
	global_load_lds_dwordx4 v[2:3], off
	v_lshl_add_u64 v[2:3], v[186:187], 0, s[10:11]
	s_mov_b32 m0, s19
	v_readfirstlane_b32 s19, v0
	v_add_u32_e32 v0, 0x14000, v198
	global_load_lds_dwordx4 v[2:3], off
	v_lshl_add_u64 v[2:3], v[188:189], 0, s[10:11]
	s_mov_b32 m0, s19
	v_readfirstlane_b32 s19, v0
	v_add_u32_e32 v0, 0x16000, v198
	global_load_lds_dwordx4 v[2:3], off
	v_lshl_add_u64 v[2:3], v[190:191], 0, s[10:11]
	s_mov_b32 m0, s19
	v_readfirstlane_b32 s19, v0
	global_load_lds_dwordx4 v[2:3], off
	v_lshl_add_u64 v[2:3], v[192:193], 0, s[10:11]
	s_mov_b32 m0, s19
	v_and_b32_e32 v199, 15, v10
	global_load_lds_dwordx4 v[2:3], off
	v_lshl_add_u64 v[186:187], v[186:187], 0, s[96:97]
	v_lshl_add_u64 v[188:189], v[188:189], 0, s[96:97]
	v_lshl_add_u64 v[190:191], v[190:191], 0, s[96:97]
	v_lshl_add_u64 v[192:193], v[192:193], 0, s[96:97]
	v_bfe_u32 v2, v10, 2, 2
	v_xor_b32_e32 v2, v196, v2
	v_lshlrev_b32_e32 v3, 6, v199
	v_ashrrev_i32_e32 v0, 7, v10
	v_and_b32_e32 v195, 1, v197
	v_lshl_or_b32 v2, v2, 4, v3
	s_waitcnt vmcnt(8)
	v_lshl_or_b32 v200, v0, 12, v2
	v_lshlrev_b32_e32 v3, 13, v195
	s_movk_i32 s19, 0x4000
	s_waitcnt lgkmcnt(0)
	s_barrier
	ds_read_b128 v[122:125], v200
	ds_read_b128 v[126:129], v200 offset:1024
	ds_read_b128 v[130:133], v200 offset:2048
	ds_read_b128 v[134:137], v200 offset:3072
	v_or3_b32 v201, v3, v2, s19
	ds_read_b128 v[150:153], v201
	ds_read_b128 v[146:149], v201 offset:1024
	ds_read_b128 v[142:145], v201 offset:2048
	ds_read_b128 v[138:141], v201 offset:3072
	v_cmp_lt_i32_e32 vcc, 3, v197
	s_and_saveexec_b64 s[20:21], vcc
	s_cbranch_execz .LBB0_181
	s_barrier

.LBB0_187:
	s_waitcnt lgkmcnt(0)
	s_cmp_gt_u32 s19, 28
	s_cselect_b64 s[26:27], -1, 0
	s_and_b64 vcc, exec, s[26:27]
	s_barrier
	s_cbranch_vccnz .LBB0_189
	s_and_b32 s28, s31, 0x18000
	s_add_i32 s28, s28, s88
	s_mov_b32 m0, s28
	s_nop 0
	global_load_lds_dwordx4 v[186:187], off
	s_add_i32 m0, s28, 0x2000
	v_lshl_add_u64 v[186:187], v[186:187], 0, 64
	global_load_lds_dwordx4 v[188:189], off
	s_add_i32 m0, s28, 0x4000
	v_lshl_add_u64 v[188:189], v[188:189], 0, 64
	global_load_lds_dwordx4 v[190:191], off
	s_add_i32 m0, s28, 0x6000
	v_lshl_add_u64 v[190:191], v[190:191], 0, 64
	global_load_lds_dwordx4 v[192:193], off
	v_lshl_add_u64 v[192:193], v[192:193], 0, 64

.LBB0_193:
	s_waitcnt lgkmcnt(0)
	s_cmp_gt_u32 s19, 27
	s_barrier
	s_cbranch_scc1 .LBB0_195
	s_add_i32 s26, s34, s88
	s_mov_b32 m0, s26
	s_nop 0
	global_load_lds_dwordx4 v[186:187], off
	s_add_i32 m0, s26, 0x2000
	v_lshl_add_u64 v[186:187], v[186:187], 0, 64
	global_load_lds_dwordx4 v[188:189], off
	s_add_i32 m0, s26, 0x4000
	v_lshl_add_u64 v[188:189], v[188:189], 0, 64
	global_load_lds_dwordx4 v[190:191], off
	s_add_i32 m0, s26, 0x6000
	v_lshl_add_u64 v[190:191], v[190:191], 0, 64
	global_load_lds_dwordx4 v[192:193], off
	v_lshl_add_u64 v[192:193], v[192:193], 0, 64
